# hg_pass1 (phase 2): item loads issued one item ahead
# baseline (speedup 1.0000x reference)
.LBB0_575:
	v_readlane_b32 s94, v245, 9
	s_mov_b64 s[4:5], s[0:1]
	s_mov_b32 s16, s94
	s_cmpk_gt_i32 s16, 0x3ff
	v_readlane_b32 s85, v245, 3
	v_readlane_b32 s88, v245, 2
	s_cbranch_scc1 .LBB0_582
	s_load_dwordx4 s[12:15], s[4:5], 0xd8
	s_load_dwordx2 s[18:19], s[4:5], 0x40
	s_mov_b32 s20, s34
	s_movk_i32 s10, 0x7f
	s_movk_i32 s11, 0x3c00
	s_waitcnt lgkmcnt(0)
	s_add_u32 s4, s14, 0x2030000
	s_addc_u32 s5, s15, 0
	s_ashr_i32 s17, s16, 31
	s_ashr_i32 s21, s34, 31
	s_lshl_b64 s[2:3], s[16:17], 9
	s_add_u32 s2, s14, s2
	s_addc_u32 s3, s15, s3
	s_add_u32 s14, s2, 0x1696800
	s_addc_u32 s15, s3, 0
	s_lshl_b64 s[22:23], s[20:21], 9
	s_lshl_b32 s2, s16, 2
	s_lshl_b32 s3, s34, 2
	s_lshl_b32 s8, s16, 6
	s_lshl_b32 s9, s34, 6
	v_mov_b64_e32 v[8:9], s[4:5]
	s_mov_b32 s25, 0
	v_mov_b32_e32 v11, 0
	s_movk_i32 s26, 0x4000
	s_movk_i32 s27, 0x7000
	s_mov_b32 s28, 0xb000
	s_mov_b32 s29, 0xf000
	s_mov_b32 s30, 0x13000
	s_mov_b32 s31, 0x16000
	s_mov_b32 s33, 0x1a000
	s_mov_b32 s36, 0x1e000
	s_mov_b32 s37, 0x22000
	s_mov_b32 s38, 0x25000
	s_mov_b32 s39, 0x29000
	s_mov_b32 s42, 0x2d000
	s_mov_b32 s43, 0x31000
	s_mov_b32 s44, 0x34000
	s_mov_b32 s45, 0x38000
	s_mov_b32 s46, 0x8000
	s_mov_b32 s47, 0x17000
	s_mov_b32 s48, 0x26000
	s_mov_b32 s49, 0x35000
	s_mov_b32 s50, 0x800000
	s_mov_b32 s51, 0x3f317217
	s_mov_b32 s52, 0x7f800000
	v_mov_b32_e32 v22, 0x41b17218
	s_movk_i32 s53, 0x7fff
	s_mov_b32 s54, 0xffff0000
	s_movk_i32 s55, 0x1100
	s_movk_i32 s56, 0x90
	s_mov_b32 s98, s16
	s_lshr_b32 s99, s98, 7
	s_lshl_b32 s99, s99, 11
	s_lshl_b32 s100, s98, 6
	s_and_b32 s100, s100, 0x7c0
	s_or_b32 s99, s99, s100
	s_lshl_b32 s100, s98, 2
	s_and_b32 s100, s100, 0x180
	v_lshrrev_b32_e32 v100, 7, v156
	v_lshl_add_u32 v100, v100, 4, s99
	v_and_b32_e32 v102, 0x7f, v156
	v_or_b32_e32 v101, s100, v102
	v_lshlrev_b32_e32 v101, 2, v101
	global_load_dword v92, v101, s[18:19] offset:2048
	global_load_dword v93, v101, s[18:19]
	s_lshl_b32 s100, s100, 1
	v_lshl_add_u32 v102, v102, 1, s100
	v_mov_b32_e32 v103, 0
	v_lshl_add_u64 v[94:95], v[102:103], 0, v[8:9]
	v_mad_u64_u32 v[94:95], vcc, v100, s11, v[94:95]
	s_mov_b32 s100, 0x3c00
	s_mov_b32 s101, 0
	global_load_ushort v60, v[94:95], off offset:1024
	global_load_ushort v61, v[94:95], off offset:2048
	v_lshl_add_u64 v[96:97], v[94:95], 0, s[100:101]
	global_load_ushort v62, v[96:97], off offset:1024
	global_load_ushort v63, v[96:97], off offset:2048
	v_lshl_add_u64 v[98:99], v[96:97], 0, s[100:101]
	global_load_ushort v64, v[98:99], off offset:1024
	global_load_ushort v65, v[98:99], off offset:2048
	v_lshl_add_u64 v[96:97], v[98:99], 0, s[100:101]
	global_load_ushort v66, v[96:97], off offset:1024
	global_load_ushort v67, v[96:97], off offset:2048
	v_lshl_add_u64 v[98:99], v[96:97], 0, s[100:101]
	global_load_ushort v68, v[98:99], off offset:1024
	global_load_ushort v69, v[98:99], off offset:2048
	v_lshl_add_u64 v[96:97], v[98:99], 0, s[100:101]
	global_load_ushort v70, v[96:97], off offset:1024
	global_load_ushort v71, v[96:97], off offset:2048
	v_lshl_add_u64 v[98:99], v[96:97], 0, s[100:101]
	global_load_ushort v72, v[98:99], off offset:1024
	global_load_ushort v73, v[98:99], off offset:2048
	v_lshl_add_u64 v[96:97], v[98:99], 0, s[100:101]
	global_load_ushort v74, v[96:97], off offset:1024
	global_load_ushort v75, v[96:97], off offset:2048
	v_lshl_add_u64 v[98:99], v[96:97], 0, s[100:101]
	global_load_ushort v76, v[98:99], off offset:1024
	global_load_ushort v77, v[98:99], off offset:2048
	v_lshl_add_u64 v[96:97], v[98:99], 0, s[100:101]
	global_load_ushort v78, v[96:97], off offset:1024
	global_load_ushort v79, v[96:97], off offset:2048
	v_lshl_add_u64 v[98:99], v[96:97], 0, s[100:101]
	global_load_ushort v80, v[98:99], off offset:1024
	global_load_ushort v81, v[98:99], off offset:2048
	v_lshl_add_u64 v[96:97], v[98:99], 0, s[100:101]
	global_load_ushort v82, v[96:97], off offset:1024
	global_load_ushort v83, v[96:97], off offset:2048
	v_lshl_add_u64 v[98:99], v[96:97], 0, s[100:101]
	global_load_ushort v84, v[98:99], off offset:1024
	global_load_ushort v85, v[98:99], off offset:2048
	v_lshl_add_u64 v[96:97], v[98:99], 0, s[100:101]
	global_load_ushort v86, v[96:97], off offset:1024
	global_load_ushort v87, v[96:97], off offset:2048
	v_lshl_add_u64 v[98:99], v[96:97], 0, s[100:101]
	global_load_ushort v88, v[98:99], off offset:1024
	global_load_ushort v89, v[98:99], off offset:2048
	v_lshl_add_u64 v[96:97], v[98:99], 0, s[100:101]
	global_load_ushort v90, v[96:97], off offset:1024
	global_load_ushort v91, v[96:97], off offset:2048
	s_waitcnt vmcnt(0)
	s_branch .LBB0_578
.LBB0_577:
	s_or_b64 exec, exec, s[6:7]
	v_bfe_u32 v28, v23, 4, 2
	v_and_b32_e32 v10, 15, v23
	v_lshl_add_u32 v6, v28, 4, 0
	v_mad_u32_u24 v29, v10, s56, v6
	s_waitcnt lgkmcnt(0)
	s_barrier
	s_add_i32 s98, s16, s20
	s_cmpk_lt_i32 s98, 0x400
	s_cselect_b32 s98, s98, s16
	s_lshr_b32 s99, s98, 7
	s_lshl_b32 s99, s99, 11
	s_lshl_b32 s100, s98, 6
	s_and_b32 s100, s100, 0x7c0
	s_or_b32 s99, s99, s100
	s_lshl_b32 s100, s98, 2
	s_and_b32 s100, s100, 0x180
	v_lshrrev_b32_e32 v100, 7, v156
	v_lshl_add_u32 v100, v100, 4, s99
	v_and_b32_e32 v102, 0x7f, v156
	v_or_b32_e32 v101, s100, v102
	v_lshlrev_b32_e32 v101, 2, v101
	global_load_dword v92, v101, s[18:19] offset:2048
	global_load_dword v93, v101, s[18:19]
	s_lshl_b32 s100, s100, 1
	v_lshl_add_u32 v102, v102, 1, s100
	v_mov_b32_e32 v103, 0
	v_lshl_add_u64 v[94:95], v[102:103], 0, v[8:9]
	v_mad_u64_u32 v[94:95], vcc, v100, s11, v[94:95]
	s_mov_b32 s100, 0x3c00
	s_mov_b32 s101, 0
	global_load_ushort v60, v[94:95], off offset:1024
	global_load_ushort v61, v[94:95], off offset:2048
	v_lshl_add_u64 v[96:97], v[94:95], 0, s[100:101]
	global_load_ushort v62, v[96:97], off offset:1024
	global_load_ushort v63, v[96:97], off offset:2048
	v_lshl_add_u64 v[98:99], v[96:97], 0, s[100:101]
	global_load_ushort v64, v[98:99], off offset:1024
	global_load_ushort v65, v[98:99], off offset:2048
	v_lshl_add_u64 v[96:97], v[98:99], 0, s[100:101]
	global_load_ushort v66, v[96:97], off offset:1024
	global_load_ushort v67, v[96:97], off offset:2048
	v_lshl_add_u64 v[98:99], v[96:97], 0, s[100:101]
	global_load_ushort v68, v[98:99], off offset:1024
	global_load_ushort v69, v[98:99], off offset:2048
	v_lshl_add_u64 v[96:97], v[98:99], 0, s[100:101]
	global_load_ushort v70, v[96:97], off offset:1024
	global_load_ushort v71, v[96:97], off offset:2048
	v_lshl_add_u64 v[98:99], v[96:97], 0, s[100:101]
	global_load_ushort v72, v[98:99], off offset:1024
	global_load_ushort v73, v[98:99], off offset:2048
	v_lshl_add_u64 v[96:97], v[98:99], 0, s[100:101]
	global_load_ushort v74, v[96:97], off offset:1024
	global_load_ushort v75, v[96:97], off offset:2048
	v_lshl_add_u64 v[98:99], v[96:97], 0, s[100:101]
	global_load_ushort v76, v[98:99], off offset:1024
	global_load_ushort v77, v[98:99], off offset:2048
	v_lshl_add_u64 v[96:97], v[98:99], 0, s[100:101]
	global_load_ushort v78, v[96:97], off offset:1024
	global_load_ushort v79, v[96:97], off offset:2048
	v_lshl_add_u64 v[98:99], v[96:97], 0, s[100:101]
	global_load_ushort v80, v[98:99], off offset:1024
	global_load_ushort v81, v[98:99], off offset:2048
	v_lshl_add_u64 v[96:97], v[98:99], 0, s[100:101]
	global_load_ushort v82, v[96:97], off offset:1024
	global_load_ushort v83, v[96:97], off offset:2048
	v_lshl_add_u64 v[98:99], v[96:97], 0, s[100:101]
	global_load_ushort v84, v[98:99], off offset:1024
	global_load_ushort v85, v[98:99], off offset:2048
	v_lshl_add_u64 v[96:97], v[98:99], 0, s[100:101]
	global_load_ushort v86, v[96:97], off offset:1024
	global_load_ushort v87, v[96:97], off offset:2048
	v_lshl_add_u64 v[98:99], v[96:97], 0, s[100:101]
	global_load_ushort v88, v[98:99], off offset:1024
	global_load_ushort v89, v[98:99], off offset:2048
	v_lshl_add_u64 v[96:97], v[98:99], 0, s[100:101]
	global_load_ushort v90, v[96:97], off offset:1024
	global_load_ushort v91, v[96:97], off offset:2048
	ds_read_b128 v[2:5], v29
	v_ashrrev_i32_e32 v7, 6, v23
	v_lshl_or_b32 v12, v7, 4, v10
	v_mad_u64_u32 v[20:21], s[4:5], v12, s56, v[6:7]
	ds_read_b128 v[12:15], v20 offset:18432
	ds_read_b128 v[16:19], v29 offset:64
	ds_read_b128 v[24:27], v20 offset:18496
	s_waitcnt lgkmcnt(2)
	v_mfma_f32_16x16x32_bf16 v[2:5], v[2:5], v[12:15], 0
	v_mul_lo_u32 v6, v7, s55
	v_add_u32_e32 v21, 0, v6
	v_lshlrev_b32_e32 v6, 3, v28
	s_waitcnt lgkmcnt(0)
	v_mfma_f32_16x16x32_bf16 v[2:5], v[16:19], v[24:27], v[2:5]
	v_mul_u32_u24_e32 v10, 0x110, v10
	v_add3_u32 v30, v21, v10, v6
	v_lshlrev_b64 v[0:1], 15, v[0:1]
	s_add_u32 s16, s16, s20
	s_addc_u32 s17, s17, s21
	s_nop 2
	v_bfe_u32 v6, v2, 16, 1
	v_add3_u32 v2, v2, v6, s53
	v_bfe_u32 v6, v3, 16, 1
	v_lshrrev_b32_e32 v2, 16, v2
	v_add3_u32 v3, v3, v6, s53
	v_and_or_b32 v2, v3, s54, v2
	v_bfe_u32 v3, v4, 16, 1
	v_add3_u32 v3, v4, v3, s53
	v_bfe_u32 v4, v5, 16, 1
	v_lshrrev_b32_e32 v3, 16, v3
	v_add3_u32 v4, v5, v4, s53
	v_and_or_b32 v3, v4, s54, v3
	ds_write_b64 v30, v[2:3] offset:38912
	ds_read_b128 v[2:5], v29 offset:2304
	ds_read_b128 v[12:15], v29 offset:2368
	ds_read_b128 v[16:19], v20 offset:18432
	ds_read_b128 v[24:27], v20 offset:18496
	s_waitcnt lgkmcnt(1)
	v_mfma_f32_16x16x32_bf16 v[2:5], v[2:5], v[16:19], 0
	s_add_u32 s14, s14, s22
	s_addc_u32 s15, s15, s23
	s_add_i32 s2, s2, s3
	s_waitcnt lgkmcnt(0)
	v_mfma_f32_16x16x32_bf16 v[2:5], v[12:15], v[24:27], v[2:5]
	s_add_i32 s8, s8, s9
	s_cmpk_lt_i32 s16, 0x400
	s_nop 5
	v_bfe_u32 v6, v2, 16, 1
	v_bfe_u32 v10, v3, 16, 1
	v_add3_u32 v2, v2, v6, s53
	v_lshrrev_b32_e32 v2, 16, v2
	v_add3_u32 v3, v3, v10, s53
	v_and_or_b32 v2, v3, s54, v2
	v_bfe_u32 v3, v4, 16, 1
	v_add3_u32 v3, v4, v3, s53
	v_bfe_u32 v4, v5, 16, 1
	v_lshrrev_b32_e32 v3, 16, v3
	v_add3_u32 v4, v5, v4, s53
	v_and_or_b32 v3, v4, s54, v3
	ds_write_b64 v30, v[2:3] offset:38944
	ds_read_b128 v[2:5], v29 offset:4608
	ds_read_b128 v[12:15], v29 offset:4672
	ds_read_b128 v[16:19], v20 offset:18432
	ds_read_b128 v[24:27], v20 offset:18496
	s_waitcnt lgkmcnt(1)
	v_mfma_f32_16x16x32_bf16 v[2:5], v[2:5], v[16:19], 0
	s_waitcnt lgkmcnt(0)
	v_mfma_f32_16x16x32_bf16 v[2:5], v[12:15], v[24:27], v[2:5]
	s_nop 7
	v_bfe_u32 v6, v2, 16, 1
	v_bfe_u32 v10, v3, 16, 1
	v_bfe_u32 v12, v4, 16, 1
	v_add3_u32 v2, v2, v6, s53
	v_add3_u32 v3, v3, v10, s53
	v_add3_u32 v4, v4, v12, s53
	v_lshrrev_b32_e32 v2, 16, v2
	v_and_or_b32 v2, v3, s54, v2
	v_lshrrev_b32_e32 v3, 16, v4
	v_bfe_u32 v4, v5, 16, 1
	v_add3_u32 v4, v5, v4, s53
	v_and_or_b32 v3, v4, s54, v3
	ds_write_b64 v30, v[2:3] offset:38976
	ds_read_b128 v[2:5], v29 offset:6912
	ds_read_b128 v[12:15], v29 offset:6976
	ds_read_b128 v[16:19], v20 offset:18432
	ds_read_b128 v[24:27], v20 offset:18496
	s_waitcnt lgkmcnt(1)
	v_mfma_f32_16x16x32_bf16 v[2:5], v[2:5], v[16:19], 0
	s_waitcnt lgkmcnt(0)
	v_mfma_f32_16x16x32_bf16 v[2:5], v[12:15], v[24:27], v[2:5]
	s_nop 7
	v_bfe_u32 v6, v2, 16, 1
	v_bfe_u32 v12, v4, 16, 1
	v_bfe_u32 v10, v3, 16, 1
	v_bfe_u32 v13, v5, 16, 1
	v_add3_u32 v2, v2, v6, s53
	v_add3_u32 v4, v4, v12, s53
	v_add3_u32 v3, v3, v10, s53
	v_add3_u32 v5, v5, v13, s53
	v_lshrrev_b32_e32 v2, 16, v2
	v_lshrrev_b32_e32 v4, 16, v4
	v_and_or_b32 v2, v3, s54, v2
	v_and_or_b32 v3, v5, s54, v4
	ds_write_b64 v30, v[2:3] offset:39008
	ds_read_b128 v[2:5], v29 offset:9216
	ds_read_b128 v[12:15], v29 offset:9280
	ds_read_b128 v[16:19], v20 offset:18432
	ds_read_b128 v[24:27], v20 offset:18496
	s_waitcnt lgkmcnt(1)
	v_mfma_f32_16x16x32_bf16 v[2:5], v[2:5], v[16:19], 0
	s_waitcnt lgkmcnt(0)
	v_mfma_f32_16x16x32_bf16 v[2:5], v[12:15], v[24:27], v[2:5]
	s_nop 7
	v_bfe_u32 v6, v2, 16, 1
	v_bfe_u32 v12, v4, 16, 1
	v_bfe_u32 v10, v3, 16, 1
	v_bfe_u32 v13, v5, 16, 1
	v_add3_u32 v2, v2, v6, s53
	v_add3_u32 v4, v4, v12, s53
	v_add3_u32 v3, v3, v10, s53
	v_add3_u32 v5, v5, v13, s53
	v_lshrrev_b32_e32 v2, 16, v2
	v_lshrrev_b32_e32 v4, 16, v4
	v_and_or_b32 v2, v3, s54, v2
	v_and_or_b32 v3, v5, s54, v4
	ds_write_b64 v30, v[2:3] offset:39040
	ds_read_b128 v[2:5], v29 offset:11520
	ds_read_b128 v[12:15], v29 offset:11584
	ds_read_b128 v[16:19], v20 offset:18432
	ds_read_b128 v[24:27], v20 offset:18496
	s_waitcnt lgkmcnt(1)
	v_mfma_f32_16x16x32_bf16 v[2:5], v[2:5], v[16:19], 0
	s_waitcnt lgkmcnt(0)
	v_mfma_f32_16x16x32_bf16 v[2:5], v[12:15], v[24:27], v[2:5]
	s_nop 7
	v_bfe_u32 v6, v2, 16, 1
	v_bfe_u32 v12, v4, 16, 1
	v_bfe_u32 v10, v3, 16, 1
	v_bfe_u32 v13, v5, 16, 1
	v_add3_u32 v2, v2, v6, s53
	v_add3_u32 v4, v4, v12, s53
	v_add3_u32 v3, v3, v10, s53
	v_add3_u32 v5, v5, v13, s53
	v_lshrrev_b32_e32 v2, 16, v2
	v_lshrrev_b32_e32 v4, 16, v4
	v_and_or_b32 v2, v3, s54, v2
	v_and_or_b32 v3, v5, s54, v4
	ds_write_b64 v30, v[2:3] offset:39072
	ds_read_b128 v[2:5], v29 offset:13824
	ds_read_b128 v[12:15], v29 offset:13888
	ds_read_b128 v[16:19], v20 offset:18432
	ds_read_b128 v[24:27], v20 offset:18496
	s_waitcnt lgkmcnt(1)
	v_mfma_f32_16x16x32_bf16 v[2:5], v[2:5], v[16:19], 0
	v_lshl_add_u64 v[16:17], s[12:13], 0, v[0:1]
	v_lshlrev_b32_e32 v6, 4, v23
	v_lshlrev_b32_e32 v18, 11, v7
	s_waitcnt lgkmcnt(0)
	v_mfma_f32_16x16x32_bf16 v[0:3], v[12:15], v[24:27], v[2:5]
	v_lshl_or_b32 v26, v28, 7, v18
	v_mul_u32_u24_e32 v23, 0x110, v28
	v_ashrrev_i32_e32 v27, 31, v26
	s_nop 4
	v_bfe_u32 v4, v0, 16, 1
	v_bfe_u32 v10, v2, 16, 1
	v_bfe_u32 v5, v1, 16, 1
	v_bfe_u32 v12, v3, 16, 1
	v_add3_u32 v0, v0, v4, s53
	v_add3_u32 v2, v2, v10, s53
	v_add3_u32 v1, v1, v5, s53
	v_add3_u32 v3, v3, v12, s53
	v_lshrrev_b32_e32 v0, 16, v0
	v_lshrrev_b32_e32 v2, 16, v2
	v_and_or_b32 v0, v1, s54, v0
	v_and_or_b32 v1, v3, s54, v2
	ds_write_b64 v30, v[0:1] offset:39104
	ds_read_b128 v[0:3], v29 offset:16128
	v_and_b32_e32 v10, 0xf0, v6
	ds_read_b128 v[4:7], v20 offset:18432
	ds_read_b128 v[12:15], v29 offset:16192
	v_lshl_add_u64 v[24:25], v[16:17], 0, v[10:11]
	ds_read_b128 v[16:19], v20 offset:18496
	s_waitcnt lgkmcnt(2)
	v_mfma_f32_16x16x32_bf16 v[0:3], v[0:3], v[4:7], 0
	v_add3_u32 v10, v21, v10, v23
	v_or_b32_e32 v20, 0x200, v26
	v_ashrrev_i32_e32 v21, 31, v20
	s_waitcnt lgkmcnt(0)
	v_mfma_f32_16x16x32_bf16 v[0:3], v[12:15], v[16:19], v[0:3]
	v_lshl_add_u64 v[12:13], v[26:27], 1, v[24:25]
	v_lshl_add_u64 v[14:15], v[20:21], 1, v[24:25]
	s_nop 5
	v_bfe_u32 v4, v0, 16, 1
	v_bfe_u32 v6, v2, 16, 1
	v_bfe_u32 v5, v1, 16, 1
	v_bfe_u32 v7, v3, 16, 1
	v_add3_u32 v0, v0, v4, s53
	v_add3_u32 v2, v2, v6, s53
	v_add3_u32 v1, v1, v5, s53
	v_add3_u32 v3, v3, v7, s53
	v_lshrrev_b32_e32 v0, 16, v0
	v_lshrrev_b32_e32 v2, 16, v2
	v_and_or_b32 v0, v1, s54, v0
	v_and_or_b32 v1, v3, s54, v2
	ds_write_b64 v30, v[0:1] offset:39136
	ds_read_b128 v[0:3], v10 offset:38912
	ds_read_b128 v[4:7], v10 offset:40000
	s_waitcnt lgkmcnt(1)
	global_store_dwordx4 v[12:13], v[0:3], off
	s_waitcnt lgkmcnt(0)
	global_store_dwordx4 v[14:15], v[4:7], off
	ds_read_b128 v[0:3], v10 offset:41088
	s_nop 0
	v_or_b32_e32 v4, 0x400, v26
	v_ashrrev_i32_e32 v5, 31, v4
	v_lshl_add_u64 v[12:13], v[4:5], 1, v[24:25]
	ds_read_b128 v[4:7], v10 offset:42176
	s_waitcnt lgkmcnt(1)
	global_store_dwordx4 v[12:13], v[0:3], off
	s_nop 1
	v_or_b32_e32 v0, 0x600, v26
	v_ashrrev_i32_e32 v1, 31, v0
	v_lshl_add_u64 v[0:1], v[0:1], 1, v[24:25]
	s_waitcnt lgkmcnt(0)
	global_store_dwordx4 v[0:1], v[4:7], off
	s_barrier
	s_cbranch_scc0 .LBB0_582
.LBB0_578:
	s_waitcnt vmcnt(8)
	v_mov_b32_e32 v23, v156
	s_ashr_i32 s4, s16, 7
	s_ashr_i32 s5, s4, 31
	s_waitcnt vmcnt(6)
	v_ashrrev_i32_e32 v25, 7, v23
	s_lshl_b64 s[4:5], s[4:5], 11
	s_and_b32 s6, s8, 0x7c0
	v_lshlrev_b32_e32 v0, 4, v25
	s_or_b32 s4, s4, s6
	v_ashrrev_i32_e32 v1, 31, v0
	v_lshl_add_u64 v[0:1], s[4:5], 0, v[0:1]
	v_mad_u64_u32 v[2:3], s[4:5], v0, s11, v[8:9]
	s_and_b32 s4, s2, 0x180
	v_and_b32_e32 v24, 0x7f, v23
	v_mad_i32_i24 v3, v1, s11, v3
	s_lshl_b32 s24, s4, 1
	v_lshl_add_u64 v[0:1], v[2:3], 0, s[24:25]
	v_or_b32_e32 v2, s4, v24
	v_lshlrev_b32_e32 v2, 2, v2
	s_waitcnt vmcnt(4)
	v_mov_b32_e32 v26, v92
	v_mov_b32_e32 v27, v93
	v_lshlrev_b32_e32 v10, 1, v24
	v_lshl_add_u64 v[0:1], v[0:1], 0, v[10:11]
	v_mov_b32_e32 v10, v60
	v_add_co_u32_e32 v2, vcc, s26, v0
	s_nop 1
	v_addc_co_u32_e32 v3, vcc, 0, v1, vcc
	v_add_co_u32_e32 v4, vcc, s27, v0
	s_nop 1
	v_addc_co_u32_e32 v5, vcc, 0, v1, vcc
	v_mov_b32_e32 v28, v62
	v_mov_b32_e32 v29, v64
	v_add_co_u32_e32 v4, vcc, s28, v0
	s_nop 1
	v_addc_co_u32_e32 v5, vcc, 0, v1, vcc
	s_waitcnt vmcnt(7)
	v_add_co_u32_e32 v6, vcc, s29, v0
	s_waitcnt vmcnt(6)
	s_nop 0
	v_addc_co_u32_e32 v7, vcc, 0, v1, vcc
	v_add_co_u32_e32 v14, vcc, s30, v0
	s_nop 1
	v_addc_co_u32_e32 v15, vcc, 0, v1, vcc
	v_add_co_u32_e32 v12, vcc, s31, v0
	s_nop 1
	v_addc_co_u32_e32 v13, vcc, 0, v1, vcc
	v_add_co_u32_e32 v16, vcc, s33, v0
	s_nop 1
	v_addc_co_u32_e32 v17, vcc, 0, v1, vcc
	v_add_co_u32_e32 v18, vcc, s36, v0
	s_nop 1
	v_addc_co_u32_e32 v19, vcc, 0, v1, vcc
	v_add_co_u32_e32 v20, vcc, s37, v0
	s_nop 1
	v_addc_co_u32_e32 v21, vcc, 0, v1, vcc
	v_mov_b32_e32 v34, v61
	s_nop 0
	v_mov_b32_e32 v13, v72
	s_nop 0
	v_mov_b32_e32 v32, v74
	v_mov_b32_e32 v33, v76
	v_mov_b32_e32 v35, v78
	s_waitcnt vmcnt(8)
	v_sub_f32_e32 v12, v26, v27
	v_mul_f32_e32 v12, 0x3fb8aa3b, v12
	v_exp_f32_e32 v12, v12
	v_mov_b32_e32 v27, v66
	v_mov_b32_e32 v36, v68
	v_mov_b32_e32 v37, v70
	v_mov_b32_e32 v38, v69
	v_mov_b32_e32 v39, v67
	v_mov_b32_e32 v40, v63
	s_waitcnt vmcnt(13)
	v_lshlrev_b32_e32 v2, 16, v10
	v_mul_f32_e32 v2, 0xbfb8aa3b, v2
	v_add_f32_e32 v3, 1.0, v12
	v_div_scale_f32 v6, s[4:5], v3, v3, 1.0
	v_rcp_f32_e32 v10, v6
	v_exp_f32_e32 v2, v2
	v_div_scale_f32 v7, vcc, 1.0, v3, 1.0
	s_waitcnt vmcnt(12)
	v_lshlrev_b32_e32 v4, 16, v28
	s_waitcnt vmcnt(11)
	v_lshlrev_b32_e32 v5, 16, v29
	v_mul_f32_e32 v4, 0xbfb8aa3b, v4
	v_mul_f32_e32 v5, 0xbfb8aa3b, v5
	v_exp_f32_e32 v4, v4
	v_exp_f32_e32 v41, v5
	v_fma_f32 v5, -v6, v10, 1.0
	v_add_f32_e32 v2, 1.0, v2
	v_fmac_f32_e32 v10, v5, v10
	v_rcp_f32_e32 v26, v2
	v_mul_f32_e32 v2, v7, v10
	v_add_f32_e32 v42, 1.0, v4
	v_fma_f32 v4, -v6, v2, v7
	v_fmac_f32_e32 v2, v4, v10
	v_fma_f32 v4, -v6, v2, v7
	v_div_fmas_f32 v2, v4, v10, v2
	v_div_fixup_f32 v10, v2, v3, 1.0
	v_add_co_u32_e32 v2, vcc, s38, v0
	v_sub_f32_e32 v12, 1.0, v10
	s_nop 0
	v_addc_co_u32_e32 v3, vcc, 0, v1, vcc
	v_add_co_u32_e32 v4, vcc, s39, v0
	s_nop 1
	v_addc_co_u32_e32 v5, vcc, 0, v1, vcc
	v_mov_b32_e32 v43, v80
	v_mov_b32_e32 v44, v82
	v_add_co_u32_e32 v2, vcc, s42, v0
	s_nop 1
	v_addc_co_u32_e32 v3, vcc, 0, v1, vcc
	v_add_co_u32_e32 v6, vcc, s43, v0
	s_nop 1
	v_addc_co_u32_e32 v7, vcc, 0, v1, vcc
	v_add_co_u32_e32 v28, vcc, s44, v0
	s_nop 1
	v_addc_co_u32_e32 v29, vcc, 0, v1, vcc
	v_mov_b32_e32 v45, v84
	v_mov_b32_e32 v46, v86
	v_mov_b32_e32 v47, v88
	v_add_co_u32_e32 v28, vcc, s45, v0
	s_nop 1
	v_addc_co_u32_e32 v29, vcc, 0, v1, vcc
	v_add_co_u32_e32 v30, vcc, s46, v0
	v_mov_b32_e32 v48, v90
	s_nop 0
	v_addc_co_u32_e32 v31, vcc, 0, v1, vcc
	v_mov_b32_e32 v49, v79
	v_mov_b32_e32 v50, v77
	v_mov_b32_e32 v51, v75
	v_mov_b32_e32 v52, v71
	v_add_co_u32_e32 v14, vcc, s47, v0
	s_nop 1
	v_addc_co_u32_e32 v15, vcc, 0, v1, vcc
	v_add_co_u32_e32 v16, vcc, s48, v0
	s_nop 1
	v_addc_co_u32_e32 v17, vcc, 0, v1, vcc
	v_mov_b32_e32 v53, v65
	v_mov_b32_e32 v54, v73
	v_mov_b32_e32 v55, v81
	v_mov_b32_e32 v56, v87
	s_nop 0
	v_mov_b32_e32 v2, v85
	s_nop 0
	v_mov_b32_e32 v3, v83
	v_add_co_u32_e32 v0, vcc, s49, v0
	s_waitcnt vmcnt(21)
	v_lshlrev_b32_e32 v4, 16, v27
	v_addc_co_u32_e32 v1, vcc, 0, v1, vcc
	v_mov_b32_e32 v57, v89
	v_mov_b32_e32 v58, v91
	v_add_f32_e32 v1, 1.0, v41
	v_mul_f32_e32 v0, 0xbfb8aa3b, v4
	v_rcp_f32_e32 v27, v1
	s_waitcnt vmcnt(22)
	v_lshlrev_b32_e32 v1, 16, v36
	v_exp_f32_e32 v0, v0
	v_mul_f32_e32 v1, 0xbfb8aa3b, v1
	v_exp_f32_e32 v1, v1
	s_waitcnt vmcnt(21)
	v_lshlrev_b32_e32 v4, 16, v37
	v_add_f32_e32 v0, 1.0, v0
	v_mul_f32_e32 v4, 0xbfb8aa3b, v4
	v_rcp_f32_e32 v15, v0
	v_add_f32_e32 v0, 1.0, v1
	v_lshlrev_b32_e32 v1, 16, v13
	v_exp_f32_e32 v4, v4
	v_mul_f32_e32 v1, 0xbfb8aa3b, v1
	v_exp_f32_e32 v1, v1
	v_rcp_f32_e32 v16, v0
	v_add_f32_e32 v0, 1.0, v4
	v_lshlrev_b32_e32 v4, 16, v32
	v_mul_f32_e32 v4, 0xbfb8aa3b, v4
	v_rcp_f32_e32 v28, v0
	v_add_f32_e32 v0, 1.0, v1
	v_lshlrev_b32_e32 v1, 16, v33
	v_exp_f32_e32 v4, v4
	v_mul_f32_e32 v1, 0xbfb8aa3b, v1
	v_exp_f32_e32 v1, v1
	v_rcp_f32_e32 v17, v0
	v_add_f32_e32 v0, 1.0, v4
	v_lshlrev_b32_e32 v4, 16, v35
	v_mul_f32_e32 v4, 0xbfb8aa3b, v4
	v_rcp_f32_e32 v29, v0
	v_add_f32_e32 v0, 1.0, v1
	v_exp_f32_e32 v4, v4
	v_rcp_f32_e32 v30, v0
	s_waitcnt vmcnt(17)
	v_lshlrev_b32_e32 v1, 16, v43
	v_mul_f32_e32 v1, 0xbfb8aa3b, v1
	v_exp_f32_e32 v1, v1
	v_add_f32_e32 v0, 1.0, v4
	s_waitcnt vmcnt(16)
	v_lshlrev_b32_e32 v4, 16, v44
	v_mul_f32_e32 v4, 0xbfb8aa3b, v4
	v_rcp_f32_e32 v32, v0
	v_add_f32_e32 v0, 1.0, v1
	v_exp_f32_e32 v4, v4
	v_rcp_f32_e32 v31, v0
	v_pk_fma_f32 v[26:27], v[12:13], v[26:27], v[10:11] op_sel_hi:[0,1,0]
	v_cmp_gt_f32_e32 vcc, s50, v26
	v_add_f32_e32 v0, 1.0, v4
	v_rcp_f32_e32 v33, v0
	v_rcp_f32_e32 v14, v42
	s_waitcnt vmcnt(15)
	v_lshlrev_b32_e32 v1, 16, v45
	v_mul_f32_e32 v1, 0xbfb8aa3b, v1
	v_exp_f32_e32 v1, v1
	s_waitcnt vmcnt(14)
	v_lshlrev_b32_e32 v4, 16, v46
	v_mul_f32_e32 v4, 0xbfb8aa3b, v4
	v_exp_f32_e32 v4, v4
	v_add_f32_e32 v0, 1.0, v1
	s_waitcnt vmcnt(13)
	v_lshlrev_b32_e32 v1, 16, v47
	v_mul_f32_e32 v1, 0xbfb8aa3b, v1
	v_exp_f32_e32 v1, v1
	v_rcp_f32_e32 v20, v0
	v_add_f32_e32 v0, 1.0, v4
	s_waitcnt vmcnt(12)
	v_lshlrev_b32_e32 v4, 16, v48
	v_rcp_f32_e32 v18, v0
	v_add_f32_e32 v0, 1.0, v1
	v_mul_f32_e32 v4, 0xbfb8aa3b, v4
	v_exp_f32_e32 v4, v4
	v_rcp_f32_e32 v21, v0
	s_waitcnt vmcnt(8)
	v_lshl_or_b32 v6, v52, 16, v38
	s_waitcnt vmcnt(7)
	v_lshl_or_b32 v5, v39, 16, v53
	v_add_f32_e32 v0, 1.0, v4
	v_lshl_or_b32 v4, v40, 16, v34
	v_rcp_f32_e32 v19, v0
	v_lshl_or_b32 v0, v49, 16, v50
	s_waitcnt vmcnt(2)
	v_lshl_or_b32 v1, v3, 16, v55
	v_cndmask_b32_e64 v3, 0, 32, vcc
	v_ldexp_f32 v3, v26, v3
	v_log_f32_e32 v13, v3
	v_lshl_or_b32 v7, v51, 16, v54
	v_lshl_add_u32 v36, v23, 2, 0
	v_lshl_add_u32 v44, v24, 2, 0
	v_mul_f32_e32 v34, 0x3f317217, v13
	v_fma_f32 v34, v13, s51, -v34
	v_fmac_f32_e32 v34, 0x3377d1cf, v13
	v_fmac_f32_e32 v34, 0x3f317217, v13
	v_cmp_lt_f32_e64 s[4:5], |v13|, s52
	v_lshl_or_b32 v2, v56, 16, v2
	s_waitcnt vmcnt(0)
	v_lshl_or_b32 v3, v58, 16, v57
	v_cndmask_b32_e64 v13, v13, v34, s[4:5]
	v_pk_fma_f32 v[34:35], v[12:13], v[14:15], v[10:11] op_sel_hi:[0,1,0]
	v_cmp_gt_f32_e64 s[4:5], s50, v34
	v_cndmask_b32_e32 v15, 0, v22, vcc
	v_sub_f32_e32 v13, v13, v15
	v_cndmask_b32_e64 v14, 0, 32, s[4:5]
	v_ldexp_f32 v14, v34, v14
	v_log_f32_e32 v14, v14
	v_add_f32_e32 v37, 0, v13
	v_cndmask_b32_e64 v15, 0, v22, s[4:5]
	v_mul_f32_e32 v13, 0x3f317217, v14
	v_fma_f32 v13, v14, s51, -v13
	v_fmac_f32_e32 v13, 0x3377d1cf, v14
	v_fmac_f32_e32 v13, 0x3f317217, v14
	v_cmp_lt_f32_e64 vcc, |v14|, s52
	s_nop 1
	v_cndmask_b32_e32 v13, v14, v13, vcc
	v_cmp_gt_f32_e32 vcc, s50, v27
	v_sub_f32_e32 v13, v13, v15
	v_add_f32_e32 v38, v37, v13
	v_cndmask_b32_e64 v14, 0, 32, vcc
	v_ldexp_f32 v14, v27, v14
	v_log_f32_e32 v14, v14
	s_nop 0
	v_mul_f32_e32 v13, 0x3f317217, v14
	v_fma_f32 v13, v14, s51, -v13
	v_fmac_f32_e32 v13, 0x3377d1cf, v14
	v_fmac_f32_e32 v13, 0x3f317217, v14
	v_cmp_lt_f32_e64 s[4:5], |v14|, s52
	s_nop 1
	v_cndmask_b32_e64 v13, v14, v13, s[4:5]
	v_cndmask_b32_e32 v14, 0, v22, vcc
	v_cmp_gt_f32_e32 vcc, s50, v35
	v_sub_f32_e32 v13, v13, v14
	v_add_f32_e32 v40, v38, v13
	v_cndmask_b32_e64 v15, 0, 32, vcc
	v_ldexp_f32 v15, v35, v15
	v_log_f32_e32 v39, v15
	v_pk_add_f32 v[14:15], v[26:27], 1.0 op_sel_hi:[1,0] neg_lo:[1,0] neg_hi:[1,0]
	v_mul_f32_e32 v13, 0x3f317217, v39
	v_fma_f32 v13, v39, s51, -v13
	v_fmac_f32_e32 v13, 0x3377d1cf, v39
	v_fmac_f32_e32 v13, 0x3f317217, v39
	v_cmp_lt_f32_e64 s[4:5], |v39|, s52
	s_nop 1
	v_cndmask_b32_e64 v13, v39, v13, s[4:5]
	v_pk_fma_f32 v[26:27], v[12:13], v[16:17], v[10:11] op_sel_hi:[0,1,0]
	v_cndmask_b32_e32 v39, 0, v22, vcc
	v_cmp_gt_f32_e32 vcc, s50, v26
	v_sub_f32_e32 v13, v13, v39
	v_add_f32_e32 v39, v40, v13
	v_cndmask_b32_e64 v16, 0, 32, vcc
	v_ldexp_f32 v16, v26, v16
	v_log_f32_e32 v41, v16
	v_pk_add_f32 v[16:17], v[34:35], 1.0 op_sel_hi:[1,0] neg_lo:[1,0] neg_hi:[1,0]
	v_cndmask_b32_e32 v35, 0, v22, vcc
	v_cmp_gt_f32_e32 vcc, s50, v27
	v_mul_f32_e32 v13, 0x3f317217, v41
	v_fma_f32 v13, v41, s51, -v13
	v_fmac_f32_e32 v13, 0x3377d1cf, v41
	v_fmac_f32_e32 v13, 0x3f317217, v41
	v_pk_fma_f32 v[28:29], v[12:13], v[28:29], v[10:11] op_sel_hi:[0,1,0]
	v_cmp_gt_f32_e64 s[4:5], s50, v28
	v_cmp_lt_f32_e64 s[6:7], |v41|, s52
	v_cndmask_b32_e32 v42, 0, v22, vcc
	v_cndmask_b32_e64 v34, 0, 32, s[4:5]
	v_ldexp_f32 v34, v28, v34
	v_log_f32_e32 v34, v34
	v_cndmask_b32_e64 v13, v41, v13, s[6:7]
	v_cndmask_b32_e64 v41, 0, 32, vcc
	v_sub_f32_e32 v13, v13, v35
	v_mul_f32_e32 v35, 0x3f317217, v34
	v_ldexp_f32 v41, v27, v41
	v_fma_f32 v35, v34, s51, -v35
	v_log_f32_e32 v41, v41
	v_fmac_f32_e32 v35, 0x3377d1cf, v34
	v_fmac_f32_e32 v35, 0x3f317217, v34
	v_cmp_lt_f32_e64 s[6:7], |v34|, s52
	v_pk_fma_f32 v[30:31], v[12:13], v[30:31], v[10:11] op_sel_hi:[0,1,0]
	v_pk_add_f32 v[26:27], v[26:27], 1.0 op_sel_hi:[1,0] neg_lo:[1,0] neg_hi:[1,0]
	v_cndmask_b32_e64 v34, v34, v35, s[6:7]
	v_cndmask_b32_e64 v35, 0, v22, s[4:5]
	v_sub_f32_e32 v34, v34, v35
	v_mul_f32_e32 v35, 0x3f317217, v41
	v_fma_f32 v35, v41, s51, -v35
	v_fmac_f32_e32 v35, 0x3377d1cf, v41
	v_fmac_f32_e32 v35, 0x3f317217, v41
	v_cmp_lt_f32_e64 s[4:5], |v41|, s52
	s_nop 1
	v_cndmask_b32_e64 v35, v41, v35, s[4:5]
	v_cmp_gt_f32_e64 s[4:5], s50, v29
	v_sub_f32_e32 v35, v35, v42
	s_nop 0
	v_cndmask_b32_e64 v41, 0, 32, s[4:5]
	v_ldexp_f32 v41, v29, v41
	v_log_f32_e32 v41, v41
	v_pk_add_f32 v[28:29], v[28:29], 1.0 op_sel_hi:[1,0] neg_lo:[1,0] neg_hi:[1,0]
	v_mul_f32_e32 v42, 0x3f317217, v41
	v_fma_f32 v42, v41, s51, -v42
	v_fmac_f32_e32 v42, 0x3377d1cf, v41
	v_fmac_f32_e32 v42, 0x3f317217, v41
	v_cmp_lt_f32_e64 vcc, |v41|, s52
	s_nop 1
	v_cndmask_b32_e32 v41, v41, v42, vcc
	v_cndmask_b32_e64 v42, 0, v22, s[4:5]
	v_cmp_gt_f32_e32 vcc, s50, v30
	v_sub_f32_e32 v41, v41, v42
	v_add_f32_e32 v42, v39, v13
	v_cndmask_b32_e64 v13, 0, 32, vcc
	v_ldexp_f32 v13, v30, v13
	v_log_f32_e32 v13, v13
	v_add_f32_e32 v43, v42, v34
	v_add_f32_e32 v45, v43, v35
	v_add_f32_e32 v46, v45, v41
	v_pk_fma_f32 v[32:33], v[12:13], v[32:33], v[10:11] op_sel_hi:[0,1,0]
	v_cmp_gt_f32_e64 s[4:5], s50, v32
	v_mul_f32_e32 v34, 0x3f317217, v13
	v_fma_f32 v34, v13, s51, -v34
	v_cndmask_b32_e64 v35, 0, 32, s[4:5]
	v_ldexp_f32 v35, v32, v35
	v_fmac_f32_e32 v34, 0x3377d1cf, v13
	v_log_f32_e32 v35, v35
	v_fmac_f32_e32 v34, 0x3f317217, v13
	v_cmp_lt_f32_e64 s[6:7], |v13|, s52
	s_nop 1
	v_cndmask_b32_e64 v13, v13, v34, s[6:7]
	v_cndmask_b32_e32 v34, 0, v22, vcc
	v_cmp_gt_f32_e32 vcc, s50, v31
	v_sub_f32_e32 v13, v13, v34
	v_mul_f32_e32 v34, 0x3f317217, v35
	v_cndmask_b32_e64 v41, 0, 32, vcc
	v_ldexp_f32 v41, v31, v41
	v_fma_f32 v34, v35, s51, -v34
	v_log_f32_e32 v41, v41
	v_fmac_f32_e32 v34, 0x3377d1cf, v35
	v_fmac_f32_e32 v34, 0x3f317217, v35
	v_cmp_lt_f32_e64 s[6:7], |v35|, s52
	v_cndmask_b32_e32 v47, 0, v22, vcc
	v_pk_fma_f32 v[20:21], v[12:13], v[20:21], v[10:11] op_sel_hi:[0,1,0]
	v_cndmask_b32_e64 v34, v35, v34, s[6:7]
	v_cndmask_b32_e64 v35, 0, v22, s[4:5]
	v_sub_f32_e32 v34, v34, v35
	v_mul_f32_e32 v35, 0x3f317217, v41
	v_fma_f32 v35, v41, s51, -v35
	v_fmac_f32_e32 v35, 0x3377d1cf, v41
	v_fmac_f32_e32 v35, 0x3f317217, v41
	v_cmp_lt_f32_e64 s[4:5], |v41|, s52
	v_pk_add_f32 v[30:31], v[30:31], 1.0 op_sel_hi:[1,0] neg_lo:[1,0] neg_hi:[1,0]
	s_nop 0
	v_cndmask_b32_e64 v35, v41, v35, s[4:5]
	v_cmp_gt_f32_e64 s[4:5], s50, v33
	v_sub_f32_e32 v35, v35, v47
	s_nop 0
	v_cndmask_b32_e64 v41, 0, 32, s[4:5]
	v_ldexp_f32 v41, v33, v41
	v_log_f32_e32 v41, v41
	v_pk_add_f32 v[32:33], v[32:33], 1.0 op_sel_hi:[1,0] neg_lo:[1,0] neg_hi:[1,0]
	v_mul_f32_e32 v47, 0x3f317217, v41
	v_fma_f32 v47, v41, s51, -v47
	v_fmac_f32_e32 v47, 0x3377d1cf, v41
	v_fmac_f32_e32 v47, 0x3f317217, v41
	v_cmp_lt_f32_e64 vcc, |v41|, s52
	s_nop 1
	v_cndmask_b32_e32 v41, v41, v47, vcc
	v_cndmask_b32_e64 v47, 0, v22, s[4:5]
	v_cmp_gt_f32_e32 vcc, s50, v20
	v_sub_f32_e32 v41, v41, v47
	v_add_f32_e32 v47, v46, v13
	v_cndmask_b32_e64 v13, 0, 32, vcc
	v_ldexp_f32 v13, v20, v13
	v_log_f32_e32 v13, v13
	v_add_f32_e32 v48, v47, v34
	v_add_f32_e32 v49, v48, v35
	v_add_f32_e32 v50, v49, v41
	v_mul_f32_e32 v34, 0x3f317217, v13
	v_fma_f32 v41, v13, s51, -v34
	v_pk_fma_f32 v[34:35], v[12:13], v[18:19], v[10:11] op_sel_hi:[0,1,0]
	v_cmp_gt_f32_e64 s[4:5], s50, v34
	v_fmac_f32_e32 v41, 0x3377d1cf, v13
	v_fmac_f32_e32 v41, 0x3f317217, v13
	v_cndmask_b32_e64 v10, 0, 32, s[4:5]
	v_ldexp_f32 v10, v34, v10
	v_log_f32_e32 v10, v10
	v_cmp_lt_f32_e64 s[6:7], |v13|, s52
	s_nop 1
	v_cndmask_b32_e64 v12, v13, v41, s[6:7]
	v_cndmask_b32_e32 v13, 0, v22, vcc
	v_cmp_gt_f32_e32 vcc, s50, v21
	v_sub_f32_e32 v12, v12, v13
	v_mul_f32_e32 v13, 0x3f317217, v10
	v_cndmask_b32_e64 v18, 0, 32, vcc
	v_fma_f32 v13, v10, s51, -v13
	v_ldexp_f32 v18, v21, v18
	v_fmac_f32_e32 v13, 0x3377d1cf, v10
	v_log_f32_e32 v18, v18
	v_fmac_f32_e32 v13, 0x3f317217, v10
	v_cmp_lt_f32_e64 s[6:7], |v10|, s52
	v_add_f32_e32 v51, v50, v12
	v_pk_add_f32 v[20:21], v[20:21], 1.0 op_sel_hi:[1,0] neg_lo:[1,0] neg_hi:[1,0]
	v_cndmask_b32_e64 v10, v10, v13, s[6:7]
	v_cndmask_b32_e64 v13, 0, v22, s[4:5]
	v_cmp_gt_f32_e64 s[4:5], s50, v35
	v_sub_f32_e32 v10, v10, v13
	v_mul_f32_e32 v13, 0x3f317217, v18
	v_cndmask_b32_e64 v19, 0, 32, s[4:5]
	v_ldexp_f32 v19, v35, v19
	v_fma_f32 v13, v18, s51, -v13
	v_log_f32_e32 v19, v19
	v_fmac_f32_e32 v13, 0x3377d1cf, v18
	v_fmac_f32_e32 v13, 0x3f317217, v18
	v_cmp_lt_f32_e64 s[6:7], |v18|, s52
	v_add_f32_e32 v10, v51, v10
	v_pk_add_f32 v[34:35], v[34:35], 1.0 op_sel_hi:[1,0] neg_lo:[1,0] neg_hi:[1,0]
	v_cndmask_b32_e64 v13, v18, v13, s[6:7]
	v_cndmask_b32_e32 v18, 0, v22, vcc
	v_sub_f32_e32 v13, v13, v18
	v_mul_f32_e32 v18, 0x3f317217, v19
	v_fma_f32 v18, v19, s51, -v18
	v_fmac_f32_e32 v18, 0x3377d1cf, v19
	v_fmac_f32_e32 v18, 0x3f317217, v19
	v_cmp_lt_f32_e64 vcc, |v19|, s52
	v_add_f32_e32 v52, v10, v13
	s_nop 0
	v_cndmask_b32_e32 v18, v19, v18, vcc
	v_cndmask_b32_e64 v19, 0, v22, s[4:5]
	v_sub_f32_e32 v18, v18, v19
	v_add_f32_e32 v53, v52, v18
	ds_write_b32 v36, v53 offset:36864
	s_waitcnt lgkmcnt(0)
	s_barrier
	ds_read2st64_b32 v[12:13], v44 offset0:144 offset1:146
	ds_read2st64_b32 v[18:19], v44 offset0:148 offset1:150
	v_cmp_gt_i32_e32 vcc, 1, v25
	v_sub_f32_e32 v39, v53, v39
	v_sub_f32_e32 v10, v53, v10
	s_waitcnt lgkmcnt(1)
	v_cndmask_b32_e32 v36, 0, v13, vcc
	v_cmp_gt_i32_e32 vcc, 2, v25
	s_waitcnt lgkmcnt(0)
	s_nop 0
	v_cndmask_b32_e32 v41, 0, v18, vcc
	v_cmp_gt_i32_e32 vcc, 3, v25
	v_add_f32_e32 v36, v36, v41
	v_lshlrev_b32_e32 v25, 5, v25
	v_cndmask_b32_e32 v41, 0, v19, vcc
	v_add_f32_e32 v54, v36, v41
	v_sub_f32_e32 v36, v53, v37
	v_sub_f32_e32 v37, v53, v38
	v_add_f32_e32 v37, v37, v54
	v_mul_f32_e32 v37, 0x3fb8aa3b, v37
	v_exp_f32_e32 v38, v37
	v_sub_f32_e32 v37, v53, v40
	v_add_f32_e32 v36, v36, v54
	v_add_f32_e32 v37, v37, v54
	v_mul_f32_e32 v36, 0x3fb8aa3b, v36
	v_mul_f32_e32 v37, 0x3fb8aa3b, v37
	v_exp_f32_e32 v36, v36
	v_exp_f32_e32 v37, v37
	v_add_f32_e32 v39, v39, v54
	v_mul_f32_e32 v39, 0x3fb8aa3b, v39
	v_sub_f32_e32 v41, v53, v43
	v_sub_f32_e32 v43, v53, v46
	v_exp_f32_e32 v39, v39
	v_add_f32_e32 v41, v41, v54
	v_add_f32_e32 v43, v43, v54
	v_mul_f32_e32 v41, 0x3fb8aa3b, v41
	v_mul_f32_e32 v43, 0x3fb8aa3b, v43
	v_pk_mul_f32 v[14:15], v[14:15], v[36:37]
	v_sub_f32_e32 v37, v53, v48
	v_sub_f32_e32 v40, v53, v42
	v_exp_f32_e32 v42, v41
	v_sub_f32_e32 v41, v53, v45
	v_exp_f32_e32 v43, v43
	v_add_f32_e32 v37, v37, v54
	v_add_f32_e32 v40, v40, v54
	v_add_f32_e32 v41, v41, v54
	v_mul_f32_e32 v37, 0x3fb8aa3b, v37
	v_mul_f32_e32 v40, 0x3fb8aa3b, v40
	v_mul_f32_e32 v41, 0x3fb8aa3b, v41
	v_pk_mul_f32 v[16:17], v[16:17], v[38:39]
	v_sub_f32_e32 v36, v53, v47
	v_exp_f32_e32 v38, v37
	v_sub_f32_e32 v37, v53, v49
	v_sub_f32_e32 v39, v53, v50
	v_add_f32_e32 v10, v10, v54
	v_exp_f32_e32 v40, v40
	v_exp_f32_e32 v41, v41
	v_add_f32_e32 v36, v36, v54
	v_add_f32_e32 v37, v37, v54
	v_add_f32_e32 v39, v39, v54
	v_mul_f32_e32 v10, 0x3fb8aa3b, v10
	v_pk_mul_f32 v[28:29], v[28:29], v[42:43]
	v_mul_f32_e32 v36, 0x3fb8aa3b, v36
	v_mul_f32_e32 v37, 0x3fb8aa3b, v37
	v_mul_f32_e32 v39, 0x3fb8aa3b, v39
	v_exp_f32_e32 v42, v10
	v_sub_f32_e32 v10, v53, v52
	v_exp_f32_e32 v36, v36
	v_exp_f32_e32 v37, v37
	v_exp_f32_e32 v39, v39
	v_add_f32_e32 v10, v10, v54
	v_mul_f32_e32 v10, 0x3fb8aa3b, v10
	v_pk_mul_f32 v[26:27], v[26:27], v[40:41]
	v_exp_f32_e32 v41, v10
	v_sub_f32_e32 v10, v53, v53
	v_sub_f32_e32 v40, v53, v51
	v_add_f32_e32 v10, v10, v54
	v_add_f32_e32 v40, v40, v54
	v_mul_f32_e32 v10, 0x3fb8aa3b, v10
	v_pk_mul_f32 v[30:31], v[30:31], v[36:37]
	v_pk_mul_f32 v[32:33], v[32:33], v[38:39]
	v_bfe_u32 v36, v28, 16, 1
	v_bfe_u32 v37, v17, 16, 1
	v_bfe_u32 v38, v16, 16, 1
	v_mul_f32_e32 v40, 0x3fb8aa3b, v40
	v_exp_f32_e32 v43, v10
	v_bfe_u32 v10, v29, 16, 1
	v_add3_u32 v38, v16, v38, s53
	v_add3_u32 v37, v17, v37, s53
	v_add3_u32 v16, v28, v36, s53
	v_bfe_u32 v17, v26, 16, 1
	v_bfe_u32 v28, v27, 16, 1
	v_exp_f32_e32 v40, v40
	v_add3_u32 v10, v29, v10, s53
	v_bfe_u32 v29, v14, 16, 1
	v_bfe_u32 v36, v15, 16, 1
	v_add3_u32 v27, v27, v28, s53
	v_add3_u32 v17, v26, v17, s53
	v_add3_u32 v15, v15, v36, s53
	v_add3_u32 v14, v14, v29, s53
	v_lshrrev_b32_e32 v26, 16, v17
	v_lshrrev_b32_e32 v17, 16, v27
	v_lshrrev_b32_e32 v14, 16, v14
	v_lshrrev_b32_e32 v15, 16, v15
	v_and_or_b32 v17, v10, s54, v17
	v_mul_u32_u24_e32 v10, 0x8c, v24
	v_pk_mul_f32 v[34:35], v[34:35], v[42:43]
	v_and_or_b32 v16, v16, s54, v26
	v_and_or_b32 v15, v37, s54, v15
	v_and_or_b32 v14, v38, s54, v14
	v_add3_u32 v10, v44, v10, v25
	v_pk_mul_f32 v[20:21], v[20:21], v[40:41]
	ds_write_b128 v10, v[14:17]
	v_bfe_u32 v15, v32, 16, 1
	v_bfe_u32 v17, v34, 16, 1
	v_add3_u32 v25, v32, v15, s53
	v_add3_u32 v26, v34, v17, s53
	v_bfe_u32 v15, v20, 16, 1
	v_bfe_u32 v17, v21, 16, 1
	v_bfe_u32 v27, v30, 16, 1
	v_bfe_u32 v28, v31, 16, 1
	v_bfe_u32 v14, v33, 16, 1
	v_bfe_u32 v16, v35, 16, 1
	v_add3_u32 v28, v31, v28, s53
	v_add3_u32 v27, v30, v27, s53
	v_add3_u32 v17, v21, v17, s53
	v_add3_u32 v15, v20, v15, s53
	v_add3_u32 v14, v33, v14, s53
	v_add3_u32 v16, v35, v16, s53
	v_lshrrev_b32_e32 v20, 16, v15
	v_lshrrev_b32_e32 v17, 16, v17
	v_lshrrev_b32_e32 v21, 16, v27
	v_lshrrev_b32_e32 v15, 16, v28
	v_and_or_b32 v15, v14, s54, v15
	v_and_or_b32 v14, v25, s54, v21
	v_and_or_b32 v17, v16, s54, v17
	v_and_or_b32 v16, v26, s54, v20
	v_cmp_lt_u32_e32 vcc, s10, v23
	ds_write_b128 v10, v[14:17] offset:16
	ds_write_b128 v10, v[4:7] offset:18432
	ds_write_b128 v10, v[0:3] offset:18448
	s_and_saveexec_b64 s[6:7], vcc
	s_xor_b64 s[6:7], exec, s[6:7]
	s_ashr_i32 s5, s16, 31
	s_mov_b32 s4, s16
	s_or_saveexec_b64 s[6:7], s[6:7]
	v_mov_b64_e32 v[0:1], s[4:5]
	s_xor_b64 exec, exec, s[6:7]
	s_cbranch_execz .LBB0_577
	v_add_f32_e32 v0, v12, v13
	v_add_f32_e32 v0, v0, v18
	v_add_f32_e32 v0, v0, v19
	v_mul_f32_e32 v0, 0x3fb8aa3b, v0
	v_exp_f32_e32 v0, v0
	v_lshlrev_b32_e32 v1, 2, v24
	global_store_dword v1, v0, s[14:15]
	v_mov_b64_e32 v[0:1], s[16:17]
	s_branch .LBB0_577
